# attention softmax max/denominator cross-row shuffles also moved from ds_bpermute to permlane swaps
# speedup vs baseline: 1.0139x; 1.0009x over previous
; #define LAS __attribute__((address_space(3)))
; __device__ __forceinline__ void attn_item(const Params& P, int half, int item, LAS unsigned char* lds, unsigned* ctr) {
;     ...
;     const int m0 = (16 * w < 96) ? 16 * w : 96;
;     f32x4 S[10];
; #pragma unroll
;     for (int jt = 0; jt < 10; ++jt) {
;         S[jt] = (f32x4){0.f, 0.f, 0.f, 0.f};
;         const LAS unsigned char* kr = Ks + (m0 + jt * 16 + c) * KSTR + 16 * g;
; #pragma unroll
;         for (int ks = 0; ks < 4; ++ks) { const bf16x8 a = *(const LAS bf16x8*)(kr + ks * 64); S[jt] = __builtin_amdgcn_mfma_f32_16x16x32_bf16(a, Qf[ks], S[jt], 0, 0, 0); }
;     }
.LBB0_539:
	s_or_b64 exec, exec, s[30:31]
	s_and_b32 s6, s6, -16
	v_and_b32_e32 v54, 15, v137
	s_min_i32 s6, s6, 0x60
	v_or_b32_e32 v18, s6, v54
	s_movk_i32 s7, 0x110
	v_mul_lo_u32 v18, v18, s7
	v_add3_u32 v55, 0, v194, v18
	ds_read_b128 v[204:207], v55
	ds_read_b128 v[208:211], v55 offset:64
	ds_read_b128 v[212:215], v55 offset:4416
	ds_read_b128 v[216:219], v55 offset:8768
	ds_read_b128 v[220:223], v55 offset:13120
	ds_read_b128 v[224:227], v55 offset:128
	s_and_b32 s5, s5, 0xff
	s_cmp_eq_u32 s5, 0
	s_cselect_b64 vcc, -1, 0
	s_mov_b32 s5, 0xff800000
	v_lshlrev_b32_e32 v194, 3, v136
	s_waitcnt lgkmcnt(5)
	v_mfma_f32_16x16x32_bf16 v[18:21], v[204:207], v[6:9], 0
	ds_read_b128 v[204:207], v55 offset:17472
	ds_read_b128 v[236:239], v55 offset:21824
	ds_read_b128 v[240:243], v55 offset:192
	s_waitcnt lgkmcnt(7)
	v_mfma_f32_16x16x32_bf16 v[18:21], v[208:211], v[14:17], v[18:21]
	ds_read_b128 v[208:211], v55 offset:26176
	ds_read_b128 v[244:247], v55 offset:30528
	ds_read_b128 v[176:179], v55 offset:4352
	s_waitcnt lgkmcnt(6)
	v_mfma_f32_16x16x32_bf16 v[18:21], v[224:227], v[2:5], v[18:21]
	ds_read_b128 v[224:227], v55 offset:34880
	ds_read_b128 v[180:183], v55 offset:4480
	ds_read_b128 v[184:187], v55 offset:4544
	s_waitcnt lgkmcnt(6)
	v_mfma_f32_16x16x32_bf16 v[18:21], v[240:243], v[10:13], v[18:21]
	ds_read_b128 v[240:243], v55 offset:8704
	ds_read_b128 v[188:191], v55 offset:8832
	s_waitcnt lgkmcnt(5)
	v_mfma_f32_16x16x32_bf16 v[22:25], v[176:179], v[6:9], 0
	v_mfma_f32_16x16x32_bf16 v[22:25], v[212:215], v[14:17], v[22:25]
	ds_read_b128 v[212:215], v55 offset:8896
	s_waitcnt lgkmcnt(4)
	v_mfma_f32_16x16x32_bf16 v[22:25], v[180:183], v[2:5], v[22:25]
	ds_read_b128 v[176:179], v55 offset:13056
	s_waitcnt lgkmcnt(4)
	v_mfma_f32_16x16x32_bf16 v[22:25], v[184:187], v[10:13], v[22:25]
	ds_read_b128 v[180:183], v55 offset:13184
	s_waitcnt lgkmcnt(4)
	v_mfma_f32_16x16x32_bf16 v[26:29], v[240:243], v[6:9], 0
	v_mfma_f32_16x16x32_bf16 v[26:29], v[216:219], v[14:17], v[26:29]
	ds_read_b128 v[216:219], v55 offset:13248
	s_waitcnt lgkmcnt(4)
	v_mfma_f32_16x16x32_bf16 v[26:29], v[188:191], v[2:5], v[26:29]
	ds_read_b128 v[240:243], v55 offset:17408
	s_waitcnt lgkmcnt(4)
	v_mfma_f32_16x16x32_bf16 v[26:29], v[212:215], v[10:13], v[26:29]
	ds_read_b128 v[212:215], v55 offset:17536
	s_waitcnt lgkmcnt(4)
	v_mfma_f32_16x16x32_bf16 v[30:33], v[176:179], v[6:9], 0
	v_mfma_f32_16x16x32_bf16 v[30:33], v[220:223], v[14:17], v[30:33]
	ds_read_b128 v[220:223], v55 offset:17600
	s_waitcnt lgkmcnt(4)
	v_mfma_f32_16x16x32_bf16 v[30:33], v[180:183], v[2:5], v[30:33]
	ds_read_b128 v[176:179], v55 offset:21760
	s_waitcnt lgkmcnt(4)
	v_mfma_f32_16x16x32_bf16 v[30:33], v[216:219], v[10:13], v[30:33]
	ds_read_b128 v[216:219], v55 offset:21888
	s_waitcnt lgkmcnt(4)
	v_mfma_f32_16x16x32_bf16 v[34:37], v[240:243], v[6:9], 0
	v_mfma_f32_16x16x32_bf16 v[34:37], v[204:207], v[14:17], v[34:37]
	ds_read_b128 v[204:207], v55 offset:21952
	s_waitcnt lgkmcnt(4)
	v_mfma_f32_16x16x32_bf16 v[34:37], v[212:215], v[2:5], v[34:37]
	ds_read_b128 v[212:215], v55 offset:26112
	s_waitcnt lgkmcnt(4)
	v_mfma_f32_16x16x32_bf16 v[34:37], v[220:223], v[10:13], v[34:37]
	ds_read_b128 v[220:223], v55 offset:26240
	s_waitcnt lgkmcnt(4)
	v_mfma_f32_16x16x32_bf16 v[38:41], v[176:179], v[6:9], 0
	v_mfma_f32_16x16x32_bf16 v[38:41], v[236:239], v[14:17], v[38:41]
	ds_read_b128 v[236:239], v55 offset:26304
	s_waitcnt lgkmcnt(4)
	v_mfma_f32_16x16x32_bf16 v[38:41], v[216:219], v[2:5], v[38:41]
	ds_read_b128 v[216:219], v55 offset:30464
	s_waitcnt lgkmcnt(4)
	v_mfma_f32_16x16x32_bf16 v[38:41], v[204:207], v[10:13], v[38:41]
	ds_read_b128 v[204:207], v55 offset:30592
	s_waitcnt lgkmcnt(4)
	v_mfma_f32_16x16x32_bf16 v[42:45], v[212:215], v[6:9], 0
	v_mfma_f32_16x16x32_bf16 v[42:45], v[208:211], v[14:17], v[42:45]
	ds_read_b128 v[208:211], v55 offset:30656
	s_waitcnt lgkmcnt(4)
	v_mfma_f32_16x16x32_bf16 v[42:45], v[220:223], v[2:5], v[42:45]
	ds_read_b128 v[212:215], v55 offset:34816
	s_waitcnt lgkmcnt(4)
	v_mfma_f32_16x16x32_bf16 v[42:45], v[236:239], v[10:13], v[42:45]
	ds_read_b128 v[220:223], v55 offset:34944
	s_waitcnt lgkmcnt(4)
	v_mfma_f32_16x16x32_bf16 v[46:49], v[216:219], v[6:9], 0
	v_mfma_f32_16x16x32_bf16 v[46:49], v[244:247], v[14:17], v[46:49]
	ds_read_b128 v[216:219], v55 offset:35008
	s_waitcnt lgkmcnt(4)
	v_mfma_f32_16x16x32_bf16 v[46:49], v[204:207], v[2:5], v[46:49]
	ds_read_b128 v[204:207], v55 offset:39168
	s_waitcnt lgkmcnt(4)
	v_mfma_f32_16x16x32_bf16 v[46:49], v[208:211], v[10:13], v[46:49]
	ds_read_b128 v[208:211], v55 offset:39232
	s_waitcnt lgkmcnt(4)
	v_mfma_f32_16x16x32_bf16 v[50:53], v[212:215], v[6:9], 0
	v_mfma_f32_16x16x32_bf16 v[50:53], v[224:227], v[14:17], v[50:53]
	ds_read_b128 v[212:215], v55 offset:39296
	s_waitcnt lgkmcnt(4)
	v_mfma_f32_16x16x32_bf16 v[50:53], v[220:223], v[2:5], v[50:53]
	ds_read_b128 v[220:223], v55 offset:39360
	s_waitcnt lgkmcnt(4)
	v_mfma_f32_16x16x32_bf16 v[50:53], v[216:219], v[10:13], v[50:53]
	s_nop 0
	s_waitcnt lgkmcnt(3)
	v_mfma_f32_16x16x32_bf16 v[6:9], v[204:207], v[6:9], 0
	s_nop 0
	s_waitcnt lgkmcnt(2)
	v_mfma_f32_16x16x32_bf16 v[6:9], v[208:211], v[14:17], v[6:9]
	s_nop 0
	s_waitcnt lgkmcnt(1)
	v_mfma_f32_16x16x32_bf16 v[2:5], v[212:215], v[2:5], v[6:9]
	s_nop 4
	s_nop 0
	s_waitcnt lgkmcnt(0)
; __device__ __forceinline__ void attn_item(const Params& P, int half, int item, LAS unsigned char* lds, unsigned* ctr) {
;     ...
;     float mx = -INFINITY;
;     const int dbase = qi + 128 - m0 - 4 * g;
;     const unsigned dlim = (unsigned)((n == 0) ? (qi < 128 ? qi : 128) : 128);
; #pragma unroll
;     for (int jt = 0; jt < 10; ++jt)
; #pragma unroll
;         for (int jj = 0; jj < 4; ++jj) { const bool ok = (unsigned)(dbase - (jt * 16 + jj)) <= dlim;
;             const float s = ok ? S[jt][jj] : -INFINITY; S[jt][jj] = s; mx = fmaxf(mx, s); }
;     mx = fmaxf(mx, __shfl_xor(mx, 16)); mx = fmaxf(mx, __shfl_xor(mx, 32));
	v_mfma_f32_16x16x32_bf16 v[2:5], v[220:223], v[10:13], v[2:5]
	v_lshlrev_b32_e32 v6, 2, v136
	v_min_i32_e32 v7, 0x80, v138
	v_mov_b32_e32 v8, 0x80
	v_or_b32_e32 v55, s6, v6
	v_cndmask_b32_e32 v7, v8, v7, vcc
	v_add_u32_e32 v8, 0x80, v138
	v_sub_u32_e32 v9, v8, v55
	v_bitop3_b32 v6, s6, v6, s6 bitop3:3
	v_cmp_le_u32_e32 vcc, v9, v7
	v_add_u32_e32 v8, v8, v6
	v_sub_u32_e32 v11, v138, v55
	v_cndmask_b32_e32 v9, v235, v18, vcc
	v_cmp_le_u32_e32 vcc, v8, v7
	v_add_u32_e32 v12, 0x7e, v11
	v_add_u32_e32 v13, 0x7d, v11
	v_cndmask_b32_e32 v8, v235, v19, vcc
	v_cmp_le_u32_e32 vcc, v12, v7
	v_add_u32_e32 v14, 0x70, v11
	v_add_u32_e32 v15, 0x6f, v11
	v_cndmask_b32_e32 v12, v235, v20, vcc
	v_cmp_le_u32_e32 vcc, v13, v7
	v_add_u32_e32 v16, 0x6e, v11
	v_add_u32_e32 v17, 0x6d, v11
	v_cndmask_b32_e32 v13, v235, v21, vcc
	v_cmp_le_u32_e32 vcc, v14, v7
	v_add_u32_e32 v18, 0x60, v11
	v_add_u32_e32 v19, 0x5f, v11
	v_cndmask_b32_e32 v14, v235, v22, vcc
	v_cmp_le_u32_e32 vcc, v15, v7
	v_add_u32_e32 v20, 0x5e, v11
	v_add_u32_e32 v21, 0x5d, v11
	v_cndmask_b32_e32 v15, v235, v23, vcc
	v_cmp_le_u32_e32 vcc, v16, v7
	v_add_u32_e32 v22, 0x50, v11
	v_add_u32_e32 v23, 0x4f, v11
	v_cndmask_b32_e32 v16, v235, v24, vcc
	v_cmp_le_u32_e32 vcc, v17, v7
	v_max3_f32 v10, v9, s5, v8
	v_max3_f32 v10, v10, v12, v13
	v_cndmask_b32_e32 v17, v235, v25, vcc
	v_cmp_le_u32_e32 vcc, v18, v7
	v_max3_f32 v10, v10, v14, v15
	v_max3_f32 v10, v10, v16, v17
	v_cndmask_b32_e32 v18, v235, v26, vcc
	v_cmp_le_u32_e32 vcc, v19, v7
	v_add_u32_e32 v6, v138, v6
	v_readlane_b32 s5, v255, 16
	v_cndmask_b32_e32 v19, v235, v27, vcc
	v_cmp_le_u32_e32 vcc, v20, v7
	v_max3_f32 v10, v10, v18, v19
	s_nop 0
	v_cndmask_b32_e32 v20, v235, v28, vcc
	v_cmp_le_u32_e32 vcc, v21, v7
	s_nop 1
	v_cndmask_b32_e32 v21, v235, v29, vcc
	v_cmp_le_u32_e32 vcc, v22, v7
	v_max3_f32 v10, v10, v20, v21
	s_nop 0
	v_cndmask_b32_e32 v22, v235, v30, vcc
	v_cmp_le_u32_e32 vcc, v23, v7
	v_add_u32_e32 v23, 0x4e, v11
	s_nop 0
	v_cndmask_b32_e32 v25, v235, v31, vcc
	v_cmp_le_u32_e32 vcc, v23, v7
	v_add_u32_e32 v23, 0x4d, v11
	v_max3_f32 v10, v10, v22, v25
	v_cndmask_b32_e32 v26, v235, v32, vcc
	v_cmp_le_u32_e32 vcc, v23, v7
	v_add_u32_e32 v23, 64, v11
	s_nop 0
	v_cndmask_b32_e32 v27, v235, v33, vcc
	v_cmp_le_u32_e32 vcc, v23, v7
	v_add_u32_e32 v23, 63, v11
	v_max3_f32 v10, v10, v26, v27
	v_cndmask_b32_e32 v28, v235, v34, vcc
	v_cmp_le_u32_e32 vcc, v23, v7
	v_add_u32_e32 v23, 62, v11
	s_nop 0
	v_cndmask_b32_e32 v29, v235, v35, vcc
	v_cmp_le_u32_e32 vcc, v23, v7
	v_add_u32_e32 v23, 61, v11
	v_max3_f32 v10, v10, v28, v29
	v_cndmask_b32_e32 v30, v235, v36, vcc
	v_cmp_le_u32_e32 vcc, v23, v7
	v_add_u32_e32 v23, 48, v11
	s_nop 0
	v_cndmask_b32_e32 v31, v235, v37, vcc
	v_cmp_le_u32_e32 vcc, v23, v7
	v_add_u32_e32 v23, 47, v11
	v_max3_f32 v10, v10, v30, v31
	v_cndmask_b32_e32 v34, v235, v38, vcc
	v_cmp_le_u32_e32 vcc, v23, v7
	v_add_u32_e32 v23, 46, v11
	s_nop 0
	v_cndmask_b32_e32 v35, v235, v39, vcc
	v_cmp_le_u32_e32 vcc, v23, v7
	v_add_u32_e32 v23, 45, v11
	v_max3_f32 v10, v10, v34, v35
	v_cndmask_b32_e32 v36, v235, v40, vcc
	v_cmp_le_u32_e32 vcc, v23, v7
	v_add_u32_e32 v23, 32, v11
	s_nop 0
	v_cndmask_b32_e32 v37, v235, v41, vcc
	v_cmp_le_u32_e32 vcc, v23, v7
	v_add_u32_e32 v23, 31, v11
	v_max3_f32 v10, v10, v36, v37
	v_cndmask_b32_e32 v38, v235, v42, vcc
	v_cmp_le_u32_e32 vcc, v23, v7
	v_add_u32_e32 v23, 30, v11
	s_nop 0
	v_cndmask_b32_e32 v39, v235, v43, vcc
	v_cmp_le_u32_e32 vcc, v23, v7
	v_add_u32_e32 v23, 29, v11
	v_max3_f32 v10, v10, v38, v39
	v_cndmask_b32_e32 v40, v235, v44, vcc
	v_cmp_le_u32_e32 vcc, v23, v7
	v_add_u32_e32 v23, 16, v11
	s_nop 0
	v_cndmask_b32_e32 v41, v235, v45, vcc
	v_cmp_le_u32_e32 vcc, v23, v7
	v_add_u32_e32 v23, 15, v11
	v_max3_f32 v10, v10, v40, v41
	v_cndmask_b32_e32 v42, v235, v46, vcc
	v_cmp_le_u32_e32 vcc, v23, v7
	v_add_u32_e32 v23, 14, v11
	s_nop 0
	v_cndmask_b32_e32 v43, v235, v47, vcc
	v_cmp_le_u32_e32 vcc, v23, v7
	v_add_u32_e32 v23, 13, v11
	v_max3_f32 v10, v10, v42, v43
	v_cndmask_b32_e32 v44, v235, v48, vcc
	v_cmp_le_u32_e32 vcc, v23, v7
	s_nop 1
	v_cndmask_b32_e32 v45, v235, v49, vcc
	v_cmp_le_u32_e32 vcc, v11, v7
	v_max3_f32 v10, v10, v44, v45
	s_nop 0
	v_cndmask_b32_e32 v46, v235, v50, vcc
	v_cmp_le_u32_e32 vcc, v6, v7
	s_nop 1
	v_cndmask_b32_e32 v47, v235, v51, vcc
	v_max3_f32 v6, v10, v46, v47
	v_add_u32_e32 v10, -2, v11
	v_cmp_le_u32_e32 vcc, v10, v7
	v_add_u32_e32 v10, -3, v11
	s_nop 0
	v_cndmask_b32_e32 v48, v235, v52, vcc
	v_cmp_le_u32_e32 vcc, v10, v7
	v_add_u32_e32 v10, -16, v11
	s_nop 0
	v_cndmask_b32_e32 v49, v235, v53, vcc
	v_cmp_le_u32_e32 vcc, v10, v7
	v_max3_f32 v6, v6, v48, v49
	s_nop 0
	v_cndmask_b32_e32 v50, v235, v2, vcc
	v_subrev_u32_e32 v2, 17, v11
	v_cmp_le_u32_e32 vcc, v2, v7
	s_nop 1
	v_cndmask_b32_e32 v51, v235, v3, vcc
	v_subrev_u32_e32 v3, 18, v11
	v_cmp_le_u32_e32 vcc, v3, v7
	v_subrev_u32_e32 v3, 19, v11
	v_max3_f32 v2, v6, v50, v51
	v_cndmask_b32_e32 v52, v235, v4, vcc
	v_and_b32_e32 v4, 64, v230
	v_cmp_le_u32_e32 vcc, v3, v7
	v_xor_b32_e32 v3, 16, v230
	v_add_u32_e32 v4, 64, v4
	v_cndmask_b32_e32 v53, v235, v5, vcc
	v_cmp_lt_i32_e32 vcc, v3, v4
	v_max3_f32 v2, v2, v52, v53
	s_nop 0
	v_cndmask_b32_e32 v3, v230, v3, vcc
	v_lshlrev_b32_e32 v56, 2, v3
	v_mov_b32_e32 v3, v2
	s_nop 1
	v_permlane16_swap_b32_e32 v3, v2
	s_nop 1
	s_waitcnt lgkmcnt(0)
	v_max_f32_e32 v3, v3, v3
	v_max_f32_e32 v2, v2, v3
	v_xor_b32_e32 v3, 32, v230
	v_cmp_lt_i32_e32 vcc, v3, v4
	s_nop 1
	v_cndmask_b32_e32 v3, v230, v3, vcc
	v_lshlrev_b32_e32 v57, 2, v3
	v_mov_b32_e32 v3, v2
	s_nop 1
	v_permlane32_swap_b32_e32 v3, v2
	s_nop 1
	s_waitcnt lgkmcnt(0)
; #define LAS __attribute__((address_space(3)))
; __device__ __forceinline__ unsigned cvt_pk_bf16(float lo, float hi) { unsigned r; asm volatile("v_cvt_pk_bf16_f32 %0, %1, %2" : "=v"(r) : "v"(lo), "v"(hi)); return r; }
; __device__ __forceinline__ void attn_item(const Params& P, int half, int item, LAS unsigned char* lds, unsigned* ctr) {
;     ...
;     float den = 0.f;
; #pragma unroll
;     for (int jt = 0; jt < 10; ++jt) { const f32x4 d = S[jt] - mx; f32x4 p; p[0] = __builtin_amdgcn_exp2f(d[0]); p[1] = __builtin_amdgcn_exp2f(d[1]); p[2] = __builtin_amdgcn_exp2f(d[2]); p[3] = __builtin_amdgcn_exp2f(d[3]);
;         S[jt] = p; den += (p[0] + p[1]) + (p[2] + p[3]); }
;     den += __shfl_xor(den, 16); den += __shfl_xor(den, 32);
;     bf16x8 Pf[5];
; #pragma unroll
;     for (int k5 = 0; k5 < 5; ++k5) { u32x4 pw; pw.x = cvt_pk_bf16(S[2 * k5][0], S[2 * k5][1]); pw.y = cvt_pk_bf16(S[2 * k5][2], S[2 * k5][3]); pw.z = cvt_pk_bf16(S[2 * k5 + 1][0], S[2 * k5 + 1][1]); pw.w = cvt_pk_bf16(S[2 * k5 + 1][2], S[2 * k5 + 1][3]); Pf[k5] = as_bf16x8(pw); }
;     const float inv = 1.0f / den;
;     bf16_t* op = Z + (size_t)qrow * ZC + colq + 4 * g;
; #pragma unroll
;     for (int dt = 0; dt < 8; ++dt) {
;         f32x4 O = (f32x4){0.f, 0.f, 0.f, 0.f};
;         const LAS unsigned char* vr = Vt + (dt * 16 + c) * VSTR + (m0 + 4 * g) * 2;
; #pragma unroll
;         for (int k5 = 0; k5 < 5; ++k5) { const u32x2 lo = *(const LAS u32x2*)(vr + k5 * 64), hi = *(const LAS u32x2*)(vr + k5 * 64 + 32);
;             const bf16x8 a = as_bf16x8((u32x4){lo.x, lo.y, hi.x, hi.y}); O = __builtin_amdgcn_mfma_f32_16x16x32_bf16(a, Pf[k5], O, 0, 0, 0); }
	v_max_f32_e32 v3, v3, v3
	v_max_f32_e32 v24, v2, v3
	v_sub_f32_e32 v2, v13, v24
	v_sub_f32_e32 v3, v12, v24
	v_sub_f32_e32 v5, v8, v24
	v_sub_f32_e32 v4, v9, v24
	v_exp_f32_e32 v4, v4
	v_exp_f32_e32 v6, v5
	v_exp_f32_e32 v5, v3
	v_exp_f32_e32 v7, v2
	v_sub_f32_e32 v9, v16, v24
	v_sub_f32_e32 v10, v15, v24
	v_sub_f32_e32 v8, v14, v24
	v_pk_add_f32 v[2:3], v[4:5], v[6:7]
	v_exp_f32_e32 v8, v8
	v_add_f32_e32 v2, v2, v3
	v_add_f32_e32 v3, 0, v2
	v_sub_f32_e32 v2, v17, v24
	v_exp_f32_e32 v10, v10
	v_exp_f32_e32 v9, v9
	v_exp_f32_e32 v11, v2
	v_sub_f32_e32 v2, v21, v24
	v_sub_f32_e32 v14, v19, v24
	v_sub_f32_e32 v15, v18, v24
	v_pk_add_f32 v[12:13], v[8:9], v[10:11]
	v_exp_f32_e32 v58, v15
	v_pk_add_f32 v[12:13], v[12:13], v[12:13] op_sel_hi:[0,1]
	v_sub_f32_e32 v12, v20, v24
	v_exp_f32_e32 v59, v14
	v_exp_f32_e32 v60, v12
	v_exp_f32_e32 v61, v2
	v_sub_f32_e32 v2, v27, v24
	v_sub_f32_e32 v12, v26, v24
	v_sub_f32_e32 v14, v25, v24
	v_sub_f32_e32 v15, v22, v24
	v_exp_f32_e32 v16, v15
	v_exp_f32_e32 v22, v14
	v_exp_f32_e32 v12, v12
	v_exp_f32_e32 v2, v2
	v_add_f32_e32 v17, v58, v59
	v_add_f32_e32 v23, v60, v61
	v_pk_add_f32 v[14:15], v[16:17], v[22:23]
	v_pk_add_f32 v[18:19], v[12:13], v[2:3]
	v_sub_f32_e32 v3, v31, v24
	v_pk_add_f32 v[14:15], v[14:15], v[18:19]
	v_sub_f32_e32 v13, v30, v24
	v_pk_add_f32 v[26:27], v[14:15], v[14:15] op_sel_hi:[0,1]
	v_sub_f32_e32 v14, v29, v24
	v_sub_f32_e32 v15, v28, v24
	v_exp_f32_e32 v28, v15
	v_exp_f32_e32 v30, v14
	v_exp_f32_e32 v29, v13
	v_exp_f32_e32 v31, v3
	v_sub_f32_e32 v3, v37, v24
	v_sub_f32_e32 v13, v36, v24
	v_exp_f32_e32 v13, v13
	v_pk_add_f32 v[14:15], v[28:29], v[30:31]
	v_exp_f32_e32 v3, v3
	v_pk_add_f32 v[32:33], v[14:15], v[14:15] op_sel_hi:[0,1]
	v_sub_f32_e32 v14, v35, v24
	v_sub_f32_e32 v15, v34, v24
	v_exp_f32_e32 v23, v15
	v_exp_f32_e32 v25, v14
	v_sub_f32_e32 v14, v41, v24
	v_sub_f32_e32 v15, v40, v24
	v_sub_f32_e32 v17, v39, v24
	v_sub_f32_e32 v18, v38, v24
	v_exp_f32_e32 v34, v18
	v_exp_f32_e32 v36, v17
	v_exp_f32_e32 v32, v15
	v_exp_f32_e32 v26, v14
	v_add_f32_e32 v35, v23, v25
	v_add_f32_e32 v37, v13, v3
	v_pk_add_f32 v[14:15], v[34:35], v[36:37]
	v_pk_add_f32 v[18:19], v[32:33], v[26:27]
	v_sub_f32_e32 v17, v43, v24
	v_pk_add_f32 v[14:15], v[14:15], v[18:19]
	v_sub_f32_e32 v18, v42, v24
	v_pk_add_f32 v[38:39], v[14:15], v[14:15] op_sel_hi:[0,1]
	v_sub_f32_e32 v14, v45, v24
	v_sub_f32_e32 v15, v44, v24
	v_exp_f32_e32 v40, v18
	v_exp_f32_e32 v42, v17
	v_exp_f32_e32 v41, v15
	v_exp_f32_e32 v43, v14
	v_sub_f32_e32 v17, v47, v24
	v_sub_f32_e32 v18, v46, v24
	v_exp_f32_e32 v27, v18
	v_pk_add_f32 v[14:15], v[40:41], v[42:43]
	v_exp_f32_e32 v33, v17
	v_pk_add_f32 v[44:45], v[14:15], v[14:15] op_sel_hi:[0,1]
	v_sub_f32_e32 v14, v49, v24
	v_sub_f32_e32 v15, v48, v24
	v_exp_f32_e32 v35, v15
	v_exp_f32_e32 v37, v14
	v_sub_f32_e32 v14, v53, v24
	v_sub_f32_e32 v15, v52, v24
	v_sub_f32_e32 v17, v51, v24
	v_sub_f32_e32 v18, v50, v24
	v_exp_f32_e32 v46, v18
	v_exp_f32_e32 v48, v17
	v_exp_f32_e32 v44, v15
	v_exp_f32_e32 v38, v14
	v_add_f32_e32 v47, v27, v33
	v_add_f32_e32 v49, v35, v37
	v_pk_add_f32 v[14:15], v[46:47], v[48:49]
	v_pk_add_f32 v[18:19], v[44:45], v[38:39]
	s_nop 0
	v_pk_add_f32 v[14:15], v[14:15], v[18:19]
	v_cvt_pk_bf16_f32 v18, v4, v6
	v_cvt_pk_bf16_f32 v19, v5, v7
	v_cvt_pk_bf16_f32 v20, v8, v10
	v_cvt_pk_bf16_f32 v21, v9, v11
	s_nop 0
	v_add_f32_e32 v14, v14, v15
	v_mov_b32_e32 v15, v14
	s_nop 1
	v_permlane16_swap_b32_e32 v15, v14
	s_nop 1
	s_waitcnt lgkmcnt(0)
	v_add_f32_e32 v39, v14, v15
	ds_bpermute_b32 v45, v57, v39
	v_cvt_pk_bf16_f32 v14, v58, v59
	v_cvt_pk_bf16_f32 v15, v60, v61
	v_cvt_pk_bf16_f32 v16, v16, v22
	v_cvt_pk_bf16_f32 v17, v12, v2
	v_cvt_pk_bf16_f32 v10, v28, v30
	v_cvt_pk_bf16_f32 v11, v29, v31
	v_cvt_pk_bf16_f32 v12, v23, v25
	s_waitcnt lgkmcnt(0)
	v_add_f32_e32 v25, v39, v45
	v_div_scale_f32 v22, s[6:7], v25, v25, 1.0
	v_rcp_f32_e32 v23, v22
	v_cvt_pk_bf16_f32 v13, v13, v3
	v_cvt_pk_bf16_f32 v6, v34, v36
	v_cvt_pk_bf16_f32 v7, v32, v26
	v_cvt_pk_bf16_f32 v8, v40, v42
	v_cvt_pk_bf16_f32 v9, v41, v43
	s_nop 0
	v_fma_f32 v26, -v22, v23, 1.0
	v_fmac_f32_e32 v23, v26, v23
	v_div_scale_f32 v26, vcc, 1.0, v25, 1.0
	v_cvt_pk_bf16_f32 v2, v27, v33
	v_mul_f32_e32 v27, v26, v23
	v_fma_f32 v28, -v22, v27, v26
	v_fmac_f32_e32 v27, v28, v23
	v_fma_f32 v22, -v22, v27, v26
	v_div_fmas_f32 v22, v22, v23, v27
	v_lshlrev_b32_e32 v27, 1, v55
	v_mul_u32_u24_e32 v28, 0x210, v54
	v_add3_u32 v27, s5, v27, v28
	v_cvt_pk_bf16_f32 v3, v35, v37
	v_cvt_pk_bf16_f32 v4, v46, v48
	v_cvt_pk_bf16_f32 v5, v44, v38
	ds_read2_b64 v[204:207], v27 offset1:4
	ds_read2_b64 v[208:211], v27 offset0:8 offset1:12
	ds_read2_b64 v[212:215], v27 offset0:16 offset1:20
	ds_read2_b64 v[216:219], v27 offset0:24 offset1:28
	ds_read2_b64 v[220:223], v27 offset0:32 offset1:36
	s_nop 0
	s_waitcnt lgkmcnt(4)
	v_mfma_f32_16x16x32_bf16 v[28:31], v[204:207], v[18:21], 0
	v_div_fixup_f32 v26, v22, v25, 1.0
	v_lshl_add_u64 v[22:23], v[130:131], 0, v[194:195]
	v_and_b32_e32 v192, 16, v230
	v_lshrrev_b32_e32 v193, 1, v192
	v_add_u32_e32 v192, v192, v193
	v_mov_b32_e32 v193, 0
	v_lshl_add_u64 v[192:193], v[22:23], 0, v[192:193]
	v_add_u32_e32 v36, 0x2000, v27
	s_waitcnt lgkmcnt(3)
	v_mfma_f32_16x16x32_bf16 v[28:31], v[208:211], v[14:17], v[28:31]
	s_nop 0
	v_cmp_eq_u32_e32 vcc, 0, v136
	s_waitcnt lgkmcnt(2)
	v_mfma_f32_16x16x32_bf16 v[28:31], v[212:215], v[10:13], v[28:31]
	s_nop 0
	s_waitcnt lgkmcnt(1)
	v_mfma_f32_16x16x32_bf16 v[28:31], v[216:219], v[6:9], v[28:31]
	s_nop 0
	s_waitcnt lgkmcnt(0)
; #define LAS __attribute__((address_space(3)))
; __device__ __forceinline__ unsigned cvt_pk_bf16(float lo, float hi) { unsigned r; asm volatile("v_cvt_pk_bf16_f32 %0, %1, %2" : "=v"(r) : "v"(lo), "v"(hi)); return r; }
; __device__ __forceinline__ void attn_item(const Params& P, int half, int item, LAS unsigned char* lds, unsigned* ctr) {
;     ...
;     const float inv = 1.0f / den;
;     bf16_t* op = Z + (size_t)qrow * ZC + colq + 4 * g;
; #pragma unroll
;     for (int dt = 0; dt < 8; ++dt) {
;         f32x4 O = (f32x4){0.f, 0.f, 0.f, 0.f};
;         const LAS unsigned char* vr = Vt + (dt * 16 + c) * VSTR + (m0 + 4 * g) * 2;
; #pragma unroll
;         for (int k5 = 0; k5 < 5; ++k5) { const u32x2 lo = *(const LAS u32x2*)(vr + k5 * 64), hi = *(const LAS u32x2*)(vr + k5 * 64 + 32);
;             const bf16x8 a = as_bf16x8((u32x4){lo.x, lo.y, hi.x, hi.y}); O = __builtin_amdgcn_mfma_f32_16x16x32_bf16(a, Pf[k5], O, 0, 0, 0); }
;         u32x2 ow; ow.x = cvt_pk_bf16(O[0] * inv, O[1] * inv); ow.y = cvt_pk_bf16(O[2] * inv, O[3] * inv);
;         *(u32x2*)(op + dt * 16) = ow;
;     }
	v_mfma_f32_16x16x32_bf16 v[28:31], v[220:223], v[2:5], v[28:31]
	s_nop 7
	v_mul_f32_e32 v28, v26, v28
	v_mul_f32_e32 v29, v26, v29
	v_cvt_pk_bf16_f32 v28, v28, v29
	v_mul_f32_e32 v29, v26, v30
	v_mul_f32_e32 v30, v26, v31
	v_cvt_pk_bf16_f32 v29, v29, v30
	v_mov_b32_e32 v248, v28
	v_mov_b32_e32 v249, v29
	ds_read2_b64 v[204:207], v36 offset0:32 offset1:36
	ds_read2_b64 v[208:211], v36 offset0:40 offset1:44
	ds_read2_b64 v[212:215], v36 offset0:48 offset1:52
	ds_read2_b64 v[216:219], v36 offset0:56 offset1:60
	ds_read2_b64 v[220:223], v36 offset0:64 offset1:68
	s_nop 0
	s_waitcnt lgkmcnt(4)
	v_mfma_f32_16x16x32_bf16 v[28:31], v[204:207], v[18:21], 0
	s_waitcnt lgkmcnt(3)
	v_mfma_f32_16x16x32_bf16 v[28:31], v[208:211], v[14:17], v[28:31]
	s_nop 0
	s_waitcnt lgkmcnt(2)
	v_mfma_f32_16x16x32_bf16 v[28:31], v[212:215], v[10:13], v[28:31]
	s_nop 0
	s_waitcnt lgkmcnt(1)
	v_mfma_f32_16x16x32_bf16 v[28:31], v[216:219], v[6:9], v[28:31]
	s_nop 0
	v_add_u32_e32 v36, 0x4000, v27
	s_waitcnt lgkmcnt(0)
	v_mfma_f32_16x16x32_bf16 v[28:31], v[220:223], v[2:5], v[28:31]
	s_nop 7
	v_mul_f32_e32 v28, v26, v28
	v_mul_f32_e32 v29, v26, v29
	v_cvt_pk_bf16_f32 v28, v28, v29
	v_mul_f32_e32 v29, v26, v30
	v_mul_f32_e32 v30, v26, v31
	v_cvt_pk_bf16_f32 v29, v29, v30
	v_mov_b32_e32 v30, v28
	v_mov_b32_e32 v31, v29
	v_mov_b32_e32 v28, v248
	v_mov_b32_e32 v29, v249
	s_nop 1
	v_permlane16_swap_b32_e32 v28, v30
	v_permlane16_swap_b32_e32 v29, v31
	global_store_dwordx4 v[192:193], v[28:31], off
	ds_read2_b64 v[204:207], v36 offset0:64 offset1:68
	ds_read2_b64 v[208:211], v36 offset0:72 offset1:76
	ds_read2_b64 v[212:215], v36 offset0:80 offset1:84
	ds_read2_b64 v[216:219], v36 offset0:88 offset1:92
	ds_read2_b64 v[220:223], v36 offset0:96 offset1:100
	s_nop 0
	s_waitcnt lgkmcnt(4)
	v_mfma_f32_16x16x32_bf16 v[28:31], v[204:207], v[18:21], 0
	s_waitcnt lgkmcnt(3)
	v_mfma_f32_16x16x32_bf16 v[28:31], v[208:211], v[14:17], v[28:31]
	s_nop 0
	s_waitcnt lgkmcnt(2)
	v_mfma_f32_16x16x32_bf16 v[28:31], v[212:215], v[10:13], v[28:31]
	s_nop 0
	s_waitcnt lgkmcnt(1)
	v_mfma_f32_16x16x32_bf16 v[28:31], v[216:219], v[6:9], v[28:31]
	s_nop 0
	v_add_u32_e32 v36, 0x6000, v27
	s_waitcnt lgkmcnt(0)
	v_mfma_f32_16x16x32_bf16 v[28:31], v[220:223], v[2:5], v[28:31]
	s_nop 7
	v_mul_f32_e32 v28, v26, v28
	v_mul_f32_e32 v29, v26, v29
	v_cvt_pk_bf16_f32 v28, v28, v29
	v_mul_f32_e32 v29, v26, v30
	v_mul_f32_e32 v30, v26, v31
	v_cvt_pk_bf16_f32 v29, v29, v30
	v_mov_b32_e32 v248, v28
	v_mov_b32_e32 v249, v29
	ds_read2_b64 v[204:207], v36 offset0:96 offset1:100
	ds_read2_b64 v[208:211], v36 offset0:104 offset1:108
	ds_read2_b64 v[212:215], v36 offset0:112 offset1:116
	ds_read2_b64 v[216:219], v36 offset0:120 offset1:124
	ds_read2_b64 v[220:223], v36 offset0:128 offset1:132
	s_nop 0
	s_waitcnt lgkmcnt(4)
	v_mfma_f32_16x16x32_bf16 v[28:31], v[204:207], v[18:21], 0
	s_waitcnt lgkmcnt(3)
	v_mfma_f32_16x16x32_bf16 v[28:31], v[208:211], v[14:17], v[28:31]
	s_nop 0
	s_waitcnt lgkmcnt(2)
	v_mfma_f32_16x16x32_bf16 v[28:31], v[212:215], v[10:13], v[28:31]
	s_nop 0
	s_waitcnt lgkmcnt(1)
	v_mfma_f32_16x16x32_bf16 v[28:31], v[216:219], v[6:9], v[28:31]
	s_nop 0
	v_add_u32_e32 v36, 0x8000, v27
	s_waitcnt lgkmcnt(0)
	v_mfma_f32_16x16x32_bf16 v[28:31], v[220:223], v[2:5], v[28:31]
	s_nop 7
	v_mul_f32_e32 v28, v26, v28
	v_mul_f32_e32 v29, v26, v29
	v_cvt_pk_bf16_f32 v28, v28, v29
	v_mul_f32_e32 v29, v26, v30
	v_mul_f32_e32 v30, v26, v31
	v_cvt_pk_bf16_f32 v29, v29, v30
	v_mov_b32_e32 v30, v28
	v_mov_b32_e32 v31, v29
	v_mov_b32_e32 v28, v248
	v_mov_b32_e32 v29, v249
	s_nop 1
	v_permlane16_swap_b32_e32 v28, v30
	v_permlane16_swap_b32_e32 v29, v31
	global_store_dwordx4 v[192:193], v[28:31], off offset:64
	ds_read2_b64 v[204:207], v36 offset0:128 offset1:132
	ds_read2_b64 v[208:211], v36 offset0:136 offset1:140
	ds_read2_b64 v[212:215], v36 offset0:144 offset1:148
	ds_read2_b64 v[216:219], v36 offset0:152 offset1:156
	ds_read2_b64 v[220:223], v36 offset0:160 offset1:164
	s_nop 0
	s_waitcnt lgkmcnt(4)
	v_mfma_f32_16x16x32_bf16 v[28:31], v[204:207], v[18:21], 0
	s_waitcnt lgkmcnt(3)
	v_mfma_f32_16x16x32_bf16 v[28:31], v[208:211], v[14:17], v[28:31]
	s_nop 0
	s_waitcnt lgkmcnt(2)
	v_mfma_f32_16x16x32_bf16 v[28:31], v[212:215], v[10:13], v[28:31]
	s_nop 0
	s_waitcnt lgkmcnt(1)
; #define LAS __attribute__((address_space(3)))
; __device__ __forceinline__ unsigned cvt_pk_bf16(float lo, float hi) { unsigned r; asm volatile("v_cvt_pk_bf16_f32 %0, %1, %2" : "=v"(r) : "v"(lo), "v"(hi)); return r; }
; __device__ __forceinline__ void attn_item(const Params& P, int half, int item, LAS unsigned char* lds, unsigned* ctr) {
;     ...
; #pragma unroll
;     for (int dt = 0; dt < 8; ++dt) {
;         f32x4 O = (f32x4){0.f, 0.f, 0.f, 0.f};
;         const LAS unsigned char* vr = Vt + (dt * 16 + c) * VSTR + (m0 + 4 * g) * 2;
; #pragma unroll
;         for (int k5 = 0; k5 < 5; ++k5) { const u32x2 lo = *(const LAS u32x2*)(vr + k5 * 64), hi = *(const LAS u32x2*)(vr + k5 * 64 + 32);
;             const bf16x8 a = as_bf16x8((u32x4){lo.x, lo.y, hi.x, hi.y}); O = __builtin_amdgcn_mfma_f32_16x16x32_bf16(a, Pf[k5], O, 0, 0, 0); }
;         u32x2 ow; ow.x = cvt_pk_bf16(O[0] * inv, O[1] * inv); ow.y = cvt_pk_bf16(O[2] * inv, O[3] * inv);
;         *(u32x2*)(op + dt * 16) = ow;
;     }
;     if (g == 0) LSE[(size_t)qrow * 12 + gi * 4 + hh] = (mx + __builtin_amdgcn_logf(den)) * 0.6931471805599453f;
	v_mfma_f32_16x16x32_bf16 v[28:31], v[216:219], v[6:9], v[28:31]
	s_nop 0
	v_add_u32_e32 v36, 0xa000, v27
	s_waitcnt lgkmcnt(0)
	v_mfma_f32_16x16x32_bf16 v[28:31], v[220:223], v[2:5], v[28:31]
	s_nop 7
	v_mul_f32_e32 v28, v26, v28
	v_mul_f32_e32 v29, v26, v29
	v_cvt_pk_bf16_f32 v28, v28, v29
	v_mul_f32_e32 v29, v26, v30
	v_mul_f32_e32 v30, v26, v31
	v_cvt_pk_bf16_f32 v29, v29, v30
	v_mov_b32_e32 v248, v28
	v_mov_b32_e32 v249, v29
	ds_read2_b64 v[204:207], v36 offset0:160 offset1:164
	ds_read2_b64 v[208:211], v36 offset0:168 offset1:172
	ds_read2_b64 v[212:215], v36 offset0:176 offset1:180
	ds_read2_b64 v[216:219], v36 offset0:184 offset1:188
	ds_read2_b64 v[220:223], v36 offset0:192 offset1:196
	s_nop 0
	s_waitcnt lgkmcnt(4)
	v_mfma_f32_16x16x32_bf16 v[28:31], v[204:207], v[18:21], 0
	s_waitcnt lgkmcnt(3)
	v_mfma_f32_16x16x32_bf16 v[28:31], v[208:211], v[14:17], v[28:31]
	s_nop 0
	s_waitcnt lgkmcnt(2)
	v_mfma_f32_16x16x32_bf16 v[28:31], v[212:215], v[10:13], v[28:31]
	s_nop 0
	s_waitcnt lgkmcnt(1)
	v_mfma_f32_16x16x32_bf16 v[28:31], v[216:219], v[6:9], v[28:31]
	s_nop 0
	v_add_u32_e32 v36, 0xc000, v27
	s_waitcnt lgkmcnt(0)
	v_mfma_f32_16x16x32_bf16 v[28:31], v[220:223], v[2:5], v[28:31]
	s_nop 7
	v_mul_f32_e32 v28, v26, v28
	v_mul_f32_e32 v29, v26, v29
	v_cvt_pk_bf16_f32 v28, v28, v29
	v_mul_f32_e32 v29, v26, v30
	v_mul_f32_e32 v30, v26, v31
	v_cvt_pk_bf16_f32 v29, v29, v30
	v_mov_b32_e32 v30, v28
	v_mov_b32_e32 v31, v29
	v_mov_b32_e32 v28, v248
	v_mov_b32_e32 v29, v249
	s_nop 1
	v_permlane16_swap_b32_e32 v28, v30
	v_permlane16_swap_b32_e32 v29, v31
	global_store_dwordx4 v[192:193], v[28:31], off offset:128
	ds_read2_b64 v[204:207], v36 offset0:192 offset1:196
	ds_read2_b64 v[208:211], v36 offset0:200 offset1:204
	ds_read2_b64 v[212:215], v36 offset0:208 offset1:212
	ds_read2_b64 v[216:219], v36 offset0:216 offset1:220
	ds_read2_b64 v[220:223], v36 offset0:224 offset1:228
	s_nop 0
	s_waitcnt lgkmcnt(4)
	v_mfma_f32_16x16x32_bf16 v[28:31], v[204:207], v[18:21], 0
	s_waitcnt lgkmcnt(3)
	v_mfma_f32_16x16x32_bf16 v[28:31], v[208:211], v[14:17], v[28:31]
	s_nop 0
	s_waitcnt lgkmcnt(2)
	v_mfma_f32_16x16x32_bf16 v[28:31], v[212:215], v[10:13], v[28:31]
	s_nop 0
	s_waitcnt lgkmcnt(1)
	v_mfma_f32_16x16x32_bf16 v[28:31], v[216:219], v[6:9], v[28:31]
	s_nop 0
	s_waitcnt lgkmcnt(0)
	v_mfma_f32_16x16x32_bf16 v[28:31], v[220:223], v[2:5], v[28:31]
	v_add_u32_e32 v32, 0xe000, v27
	s_nop 6
	v_mul_f32_e32 v28, v26, v28
	v_mul_f32_e32 v29, v26, v29
	v_cvt_pk_bf16_f32 v28, v28, v29
	v_mul_f32_e32 v29, v26, v30
	v_mul_f32_e32 v30, v26, v31
	v_cvt_pk_bf16_f32 v29, v29, v30
	v_mov_b32_e32 v248, v28
	v_mov_b32_e32 v249, v29
	ds_read2_b64 v[28:31], v32 offset0:224 offset1:228
	s_waitcnt lgkmcnt(0)
	v_mfma_f32_16x16x32_bf16 v[18:21], v[28:31], v[18:21], 0
	ds_read2_b64 v[28:31], v32 offset0:232 offset1:236
	s_waitcnt lgkmcnt(0)
	v_mfma_f32_16x16x32_bf16 v[14:17], v[28:31], v[14:17], v[18:21]
	s_nop 4
	ds_read2_b64 v[18:21], v32 offset0:240 offset1:244
	s_waitcnt lgkmcnt(0)
	v_mfma_f32_16x16x32_bf16 v[10:13], v[18:21], v[10:13], v[14:17]
	s_nop 2
	ds_read2_b64 v[14:17], v32 offset0:248 offset1:252
	s_waitcnt lgkmcnt(0)
	v_mfma_f32_16x16x32_bf16 v[6:9], v[14:17], v[6:9], v[10:13]
	s_nop 2
	v_add_u32_e32 v10, 0xe800, v27
	ds_read2_b64 v[10:13], v10 offset1:4
	s_waitcnt lgkmcnt(0)
	v_mfma_f32_16x16x32_bf16 v[2:5], v[10:13], v[2:5], v[6:9]
	s_nop 7
	v_mul_f32_e32 v2, v26, v2
	v_mul_f32_e32 v3, v26, v3
	v_cvt_pk_bf16_f32 v2, v2, v3
	v_mul_f32_e32 v3, v26, v4
	v_mul_f32_e32 v4, v26, v5
	v_cvt_pk_bf16_f32 v3, v3, v4
	v_mov_b32_e32 v30, v2
	v_mov_b32_e32 v31, v3
	v_mov_b32_e32 v28, v248
	v_mov_b32_e32 v29, v249
	s_nop 1
	v_permlane16_swap_b32_e32 v28, v30
	v_permlane16_swap_b32_e32 v29, v31
	global_store_dwordx4 v[192:193], v[28:31], off offset:192
	s_and_saveexec_b64 s[30:31], vcc
	s_cbranch_execz .LBB0_541
	v_log_f32_e32 v2, v25
	v_readlane_b32 s8, v251, 33
	s_lshl_b32 s6, s2, 2
	v_readlane_b32 s9, v251, 34
	v_add_f32_e32 v2, v24, v2
	s_ashr_i32 s7, s6, 31
	v_mul_f32_e32 v4, 0x3f317218, v2
	v_mad_i64_i32 v[2:3], s[8:9], v133, 48, s[8:9]
	v_lshl_add_u64 v[2:3], s[6:7], 2, v[2:3]
	s_lshl_b32 s20, s4, 2
	v_lshl_add_u64 v[2:3], v[2:3], 0, s[20:21]
	global_store_dword v[2:3], v4, off

; __device__ __forceinline__ float bflo(unsigned w) { return __uint_as_float(w << 16); }
; __device__ __forceinline__ float bfhi(unsigned w) { return __uint_as_float(w & 0xffff0000u); }
; __device__ void phase_resid(const float* xin, float* xout, const bf16_t* Y, const float* pg, const float* ng, bf16_t* H2, int nrows) {
;     ...
;     for (; row < nrows; row += stride) {
;         f32x4 y[4], xv[4];
; #pragma unroll
;         for (int i = 0; i < 4; ++i) { y[i] = (f32x4){bflo(ny[i].x), bfhi(ny[i].x), bflo(ny[i].y), bfhi(ny[i].y)}; xv[i] = nx[i]; }
;         const int rn = row + stride;
;         if (rn < nrows) {
; #pragma unroll
;             for (int i = 0; i < 4; ++i) { ny[i] = *(const u32x2*)(Y + (size_t)rn * DM + i * 256 + lane * 4); nx[i] = *(const f32x4*)(xin + (size_t)rn * DM + i * 256 + lane * 4); }
;         }
;         float ss = 0.f;
; #pragma unroll
;         for (int i = 0; i < 4; ++i) ss += y[i][0] * y[i][0] + y[i][1] * y[i][1] + y[i][2] * y[i][2] + y[i][3] * y[i][3];
;         ss = wave_sum(ss);
;         const float r = rsqrtf(ss * (1.0f / DM) + EPS);
;         float s2 = 0.f;
; #pragma unroll
;         for (int i = 0; i < 4; ++i) { xv[i] = xv[i] + y[i] * r * pgv[i]; *(f32x4*)(xout + (size_t)row * DM + i * 256 + lane * 4) = xv[i];
;             s2 += xv[i][0] * xv[i][0] + xv[i][1] * xv[i][1] + xv[i][2] * xv[i][2] + xv[i][3] * xv[i][3]; }
.LBB0_609:
	s_or_b64 exec, exec, s[38:39]
	v_and_b32_e32 v83, 0xffff0000, v72
	v_and_b32_e32 v82, 0xffff0000, v70
	v_lshlrev_b32_e32 v81, 16, v72
	v_lshlrev_b32_e32 v80, 16, v70
	v_lshlrev_b32_e32 v84, 16, v71
	v_and_b32_e32 v72, 0xffff0000, v71
	v_lshlrev_b32_e32 v71, 16, v68
	v_lshlrev_b32_e32 v70, 16, v66
	s_waitcnt lgkmcnt(1)
	v_and_b32_e32 v87, 0xffff0000, v68
	v_and_b32_e32 v86, 0xffff0000, v66
	v_lshlrev_b32_e32 v88, 16, v67
	v_and_b32_e32 v68, 0xffff0000, v67
	v_pk_mul_f32 v[66:67], v[82:83], v[82:83]
	v_lshlrev_b32_e32 v85, 16, v73
	v_pk_fma_f32 v[66:67], v[80:81], v[80:81], v[66:67]
	v_pk_mul_f32 v[90:91], v[86:87], v[86:87]
	v_and_b32_e32 v73, 0xffff0000, v73
	v_lshlrev_b32_e32 v89, 16, v69
	v_pk_fma_f32 v[66:67], v[84:85], v[84:85], v[66:67]
	v_pk_fma_f32 v[90:91], v[70:71], v[70:71], v[90:91]
	v_and_b32_e32 v69, 0xffff0000, v69
	v_pk_fma_f32 v[66:67], v[72:73], v[72:73], v[66:67]
	v_pk_fma_f32 v[90:91], v[88:89], v[88:89], v[90:91]
	v_add_f32_e32 v66, v66, v67
	v_pk_fma_f32 v[90:91], v[68:69], v[68:69], v[90:91]
	s_and_b64 s[0:1], exec, vcc
	v_add_f32_e32 v66, v66, v90
	v_add_f32_e32 v66, v66, v91
	v_mov_b32_e32 v67, v66
	s_nop 1
	v_permlane32_swap_b32_e32 v67, v66
	s_nop 1
	v_mov_b32_e32 v90, v80
	v_mov_b32_e32 v93, v72
	v_mov_b32_e32 v92, v84
	s_or_b64 s[36:37], s[0:1], s[36:37]
	s_waitcnt lgkmcnt(0)
	v_add_f32_e32 v66, v66, v67
	v_mov_b32_e32 v67, v66
	s_nop 1
	v_permlane16_swap_b32_e32 v67, v66
	s_nop 1
	v_lshl_add_u64 v[56:57], v[56:57], 0, s[22:23]
	v_lshl_add_u64 v[54:55], v[54:55], 0, s[70:71]
	s_waitcnt lgkmcnt(0)
	v_add_f32_e32 v66, v66, v67
	s_nop 1
	v_mov_b32_dpp v67, v66 row_ror:8 row_mask:0xf bank_mask:0xf
	s_waitcnt lgkmcnt(0)
	v_add_f32_e32 v66, v66, v67
	s_nop 1
	v_mov_b32_dpp v67, v66 row_shl:4 row_mask:0xf bank_mask:0x5
	s_nop 1
	v_mov_b32_dpp v67, v66 row_shr:4 row_mask:0xf bank_mask:0xa
	s_waitcnt lgkmcnt(0)
	v_add_f32_e32 v66, v66, v67
	s_nop 1
	v_mov_b32_dpp v67, v66 quad_perm:[2,3,0,1] row_mask:0xf bank_mask:0xf
	s_waitcnt lgkmcnt(0)
	v_add_f32_e32 v79, v66, v67
	s_nop 1
	v_mov_b32_dpp v91, v79 quad_perm:[1,0,3,2] row_mask:0xf bank_mask:0xf
	v_lshl_add_u64 v[66:67], v[52:53], 0, v[194:195]
	v_lshl_add_u64 v[52:53], v[52:53], 0, s[70:71]
	s_waitcnt lgkmcnt(0)
	v_add_f32_e32 v79, v79, v91
	v_fmamk_f32 v79, v79, 0x3a800000, v1
	v_mul_f32_e32 v80, 0x4b800000, v79
	v_cmp_gt_f32_e32 vcc, s33, v79
	v_mov_b32_e32 v91, v82
	v_mov_b32_e32 v82, v81
	v_cndmask_b32_e32 v79, v79, v80, vcc
	v_rsq_f32_e32 v79, v79
	s_nop 0
	v_mul_f32_e32 v72, 0x45800000, v79
	v_cndmask_b32_e32 v80, v79, v72, vcc
	v_pk_mul_f32 v[90:91], v[80:81], v[90:91] op_sel_hi:[0,1]
	v_pk_mul_f32 v[92:93], v[80:81], v[92:93] op_sel_hi:[0,1]
	v_pk_fma_f32 v[32:33], v[4:5], v[92:93], v[32:33]
	v_pk_fma_f32 v[30:31], v[2:3], v[90:91], v[30:31]
	v_mov_b32_e32 v72, v85
	global_store_dwordx4 v[66:67], v[30:33], off
	s_nop 1
	v_pk_mul_f32 v[30:31], v[80:81], v[82:83] op_sel_hi:[0,1]
	v_pk_mul_f32 v[32:33], v[80:81], v[72:73] op_sel_hi:[0,1]
	v_pk_fma_f32 v[28:29], v[8:9], v[32:33], v[28:29]
	v_pk_fma_f32 v[26:27], v[6:7], v[30:31], v[26:27]
	global_store_dwordx4 v[66:67], v[26:29], off offset:1024
	s_waitcnt vmcnt(9)
	v_mov_b64_e32 v[30:31], v[34:35]
	v_mov_b64_e32 v[32:33], v[36:37]
	v_mov_b32_e32 v26, v70
	v_mov_b32_e32 v27, v86
	v_mov_b32_e32 v28, v88
	v_mov_b32_e32 v29, v68
	v_pk_mul_f32 v[26:27], v[80:81], v[26:27] op_sel_hi:[0,1]
	v_pk_mul_f32 v[28:29], v[80:81], v[28:29] op_sel_hi:[0,1]
	s_waitcnt vmcnt(3)
	v_pk_fma_f32 v[24:25], v[12:13], v[28:29], v[24:25]
	v_pk_fma_f32 v[22:23], v[10:11], v[26:27], v[22:23]
	v_mov_b32_e32 v86, v71
	v_mov_b32_e32 v68, v89
	global_store_dwordx4 v[66:67], v[22:25], off offset:2048
	v_mov_b64_e32 v[26:27], v[38:39]
	v_mov_b64_e32 v[28:29], v[40:41]
	v_pk_mul_f32 v[22:23], v[80:81], v[86:87] op_sel_hi:[0,1]
	v_pk_mul_f32 v[24:25], v[80:81], v[68:69] op_sel_hi:[0,1]
	s_waitcnt vmcnt(3)
	v_pk_fma_f32 v[20:21], v[16:17], v[24:25], v[20:21]
	v_pk_fma_f32 v[18:19], v[14:15], v[22:23], v[18:19]
	global_store_dwordx4 v[66:67], v[18:21], off offset:3072
	v_mov_b64_e32 v[22:23], v[46:47]
	v_mov_b64_e32 v[24:25], v[48:49]
	v_mov_b64_e32 v[18:19], v[42:43]
	v_mov_b64_e32 v[20:21], v[44:45]
	v_mov_b64_e32 v[70:71], v[58:59]
	v_mov_b64_e32 v[72:73], v[60:61]
	v_mov_b64_e32 v[66:67], v[62:63]
	v_mov_b64_e32 v[68:69], v[64:65]
	s_andn2_b64 exec, exec, s[36:37]
	s_cbranch_execz .LBB0_612
